# deferred layer-1 weight conversion split retuned: 3 items per idle CU in the in-projection tail, 6 in the up-projection tail (was 4/5)
# baseline (speedup 1.0000x reference)
; #define LAS __attribute__((address_space(3)))
; DI int otid() { int t = threadIdx.x; asm volatile("" : "+v"(t)); return t; }
; DI void prep_items(const Params& p, LAS unsigned char* lds, int l, unsigned* ctr, int max_items) {
;     const int tid = otid(), lane = tid & 63, wid = tid >> 6;
;     LAS float* s_c = (LAS float*)lds;
;     LAS float* s_red = (LAS float*)(lds + 40960);
;     volatile LAS int* slot = (volatile LAS int*)(lds + LDS_CTRL + 64);
;     constexpr int N_ADA = 48, PER_L = 12832, N_CONV = PER_L / 8;
;     const int n_tab = (l == 0) ? 48 : 0;
;     float* mod = (float*)(p.ws + WS_MOD);
;     bool have_c = false;
;     for (int done = 0; done < max_items; ++done) {
;         const int it = next_item(ctr, slot);
;         if (it >= N_ADA + n_tab + N_CONV) break;
;     ...
;             int id = (it - N_ADA - n_tab) * 8 + wid;
;             if (id < 3072) conv_witem(p.in[6] + (size_t)l * 2048 * INW, 2048, INW, (bf16_t*)(p.ws + WS_WIN) + (size_t)l * 6144 * 2048, nullptr, true, id % 128, id / 128, lane);
;             else if ((id -= 3072) < 128) conv_witem(p.in[9] + (size_t)l * 512 * 960, 512, 960, (bf16_t*)(p.ws + WS_WUQ) + (size_t)l * 1024 * 512, p.in[7] + l * 512, false, id % 32, id / 32, lane);
;             else if ((id -= 128) < 160) conv_witem(p.in[10] + (size_t)l * 512 * 1280, 512, 1280, (bf16_t*)(p.ws + WS_WUKV) + (size_t)l * 1280 * 512, p.in[8] + l * 512, false, id % 32, id / 32, lane);
;             else if ((id -= 160) < 1024) conv_witem(p.in[13] + (size_t)l * 2048 * 2048, 2048, 2048, (bf16_t*)(p.ws + WS_WO) + (size_t)l * 2048 * 2048, nullptr, false, id % 128, id / 128, lane);
;             else if ((id -= 1024) < 5632) conv_witem(p.in[16] + (size_t)l * 2048 * 11264, 2048, 11264, (bf16_t*)(p.ws + WS_WUP) + (size_t)l * 11264 * 2048, nullptr, false, id % 128, id / 128, lane, true);
;             else { id -= 5632; conv_witem(p.in[19] + (size_t)l * 5632 * 2048, 5632, 2048, (bf16_t*)(p.ws + WS_WDN) + (size_t)l * 2048 * 5632, nullptr, false, id % 352, id / 352, lane); }
.LBB0_922:
	s_cmpk_lt_u32 s26, 96
	s_cbranch_scc1 .Ldef_skip_1
	v_writelane_b32 v254, s0, 0
	v_writelane_b32 v254, s1, 1
	v_writelane_b32 v254, s2, 2
	v_writelane_b32 v254, s3, 3
	v_writelane_b32 v254, s4, 4
	v_writelane_b32 v254, s5, 5
	v_writelane_b32 v254, s6, 6
	v_writelane_b32 v254, s7, 7
	v_writelane_b32 v254, s8, 8
	v_writelane_b32 v254, s9, 9
	v_writelane_b32 v254, s10, 10
	v_writelane_b32 v254, s11, 11
	v_writelane_b32 v254, s12, 12
	v_writelane_b32 v254, s13, 13
	v_writelane_b32 v254, s14, 14
	v_writelane_b32 v254, s15, 15
	v_writelane_b32 v254, s16, 16
	v_writelane_b32 v254, s17, 17
	v_writelane_b32 v254, s18, 18
	v_writelane_b32 v254, s19, 19
	v_writelane_b32 v254, s20, 20
	v_writelane_b32 v254, s21, 21
	v_writelane_b32 v254, s22, 22
	v_writelane_b32 v254, s23, 23
	v_writelane_b32 v254, s24, 24
	v_writelane_b32 v254, s25, 25
	v_writelane_b32 v254, s26, 26
	v_writelane_b32 v254, s27, 27
	v_writelane_b32 v254, s28, 28
	v_writelane_b32 v254, s29, 29
	v_writelane_b32 v254, s30, 30
	v_writelane_b32 v254, s31, 31
	v_writelane_b32 v254, s32, 32
	v_writelane_b32 v254, s33, 33
	v_writelane_b32 v254, s34, 34
	v_writelane_b32 v254, s35, 35
	v_writelane_b32 v254, s36, 36
	v_writelane_b32 v254, s37, 37
	v_writelane_b32 v254, s38, 38
	v_writelane_b32 v254, s39, 39
	v_writelane_b32 v254, s40, 40
	v_writelane_b32 v254, s41, 41
	v_writelane_b32 v254, s42, 42
	v_writelane_b32 v254, s43, 43
	v_writelane_b32 v254, s44, 44
	v_writelane_b32 v254, s45, 45
	v_writelane_b32 v254, s46, 46
	v_writelane_b32 v254, s47, 47
	v_writelane_b32 v254, s48, 48
	v_writelane_b32 v254, s49, 49
	v_writelane_b32 v254, s50, 50
	v_writelane_b32 v254, s51, 51
	v_writelane_b32 v254, s52, 52
	v_writelane_b32 v254, s53, 53
	v_writelane_b32 v254, s54, 54
	v_writelane_b32 v254, s55, 55
	v_writelane_b32 v254, s56, 56
	v_writelane_b32 v254, s57, 57
	v_writelane_b32 v254, s58, 58
	v_writelane_b32 v254, s59, 59
	v_writelane_b32 v254, s60, 60
	v_writelane_b32 v254, s61, 61
	v_writelane_b32 v254, s62, 62
	v_writelane_b32 v254, s63, 63
	v_writelane_b32 v255, s64, 0
	v_writelane_b32 v255, s65, 1
	v_writelane_b32 v255, s66, 2
	v_writelane_b32 v255, s67, 3
	v_writelane_b32 v255, s68, 4
	v_writelane_b32 v255, s69, 5
	v_writelane_b32 v255, s70, 6
	v_writelane_b32 v255, s71, 7
	v_writelane_b32 v255, s72, 8
	v_writelane_b32 v255, s73, 9
	v_writelane_b32 v255, s74, 10
	v_writelane_b32 v255, s75, 11
	v_writelane_b32 v255, s76, 12
	v_writelane_b32 v255, s77, 13
	v_writelane_b32 v255, s78, 14
	v_writelane_b32 v255, s79, 15
	v_writelane_b32 v255, s80, 16
	v_writelane_b32 v255, s81, 17
	v_writelane_b32 v255, s82, 18
	v_writelane_b32 v255, s83, 19
	v_writelane_b32 v255, s84, 20
	v_writelane_b32 v255, s85, 21
	v_writelane_b32 v255, s86, 22
	v_writelane_b32 v255, s87, 23
	v_writelane_b32 v255, s88, 24
	v_writelane_b32 v255, s89, 25
	v_writelane_b32 v255, s90, 26
	v_writelane_b32 v255, s91, 27
	v_writelane_b32 v255, s92, 28
	v_writelane_b32 v255, s93, 29
	v_writelane_b32 v255, s94, 30
	v_writelane_b32 v255, s95, 31
	v_writelane_b32 v255, s96, 32
	v_writelane_b32 v255, s97, 33
	v_readlane_b32 s2, v253, 9
	s_nop 0
	v_writelane_b32 v255, s2, 40
	v_readlane_b32 s2, v253, 10
	s_nop 0
	v_writelane_b32 v255, s2, 41
	v_readlane_b32 s2, v253, 13
	s_nop 0
	v_writelane_b32 v255, s2, 42
	v_readlane_b32 s2, v253, 14
	s_nop 0
	v_writelane_b32 v255, s2, 43
	v_readlane_b32 s2, v253, 15
	s_nop 0
	v_writelane_b32 v255, s2, 44
	v_readlane_b32 s2, v253, 16
	s_nop 0
	v_writelane_b32 v255, s2, 45
	v_readlane_b32 s2, v253, 17
	s_nop 0
	v_writelane_b32 v255, s2, 46
	v_readlane_b32 s2, v253, 18
	s_nop 0
	v_writelane_b32 v255, s2, 47
	v_readlane_b32 s2, v255, 62
	v_readlane_b32 s3, v255, 63
	s_nop 4
	s_load_dwordx16 s[36:51], s[2:3], 0x80
	s_load_dwordx16 s[68:83], s[2:3], 0x0
	s_load_dwordx16 s[52:67], s[2:3], 0x40
	s_mov_b32 s4, -1
	s_nop 0
	v_writelane_b32 v253, s4, 9
	v_writelane_b32 v253, s4, 10
	v_writelane_b32 v253, s4, 13
	v_writelane_b32 v253, s4, 14
	s_waitcnt lgkmcnt(0)
	s_add_u32 s14, s50, 0x8000
	s_addc_u32 s15, s51, 0
	s_add_u32 s0, s50, 0x4600
	s_addc_u32 s1, s51, 0
	v_mov_b32_e32 v68, v202
	s_movk_i32 s6, 0x3000
	s_movk_i32 s94, 0x1400
	v_or_b32_sdwa v90, v68, s6 dst_sel:DWORD dst_unused:UNUSED_PAD src0_sel:BYTE_0 src1_sel:DWORD
	s_add_u32 s6, s42, 0x2c00000
	s_addc_u32 s7, s43, 0
	s_add_u32 s22, s50, 0xb5a0000
	s_addc_u32 s23, s51, 0
	s_add_u32 s28, s36, 0x5800000
	v_writelane_b32 v253, s6, 17
	s_addc_u32 s29, s37, 0
	v_and_b32_e32 v0, 63, v68
	v_writelane_b32 v253, s7, 18
	s_add_u32 s6, s50, 0x73a0000
	s_addc_u32 s7, s51, 0
	s_add_u32 s34, s62, 0x1000000
	s_addc_u32 s35, s63, 0
	s_add_u32 s36, s50, 0x3fa0000
	s_addc_u32 s37, s51, 0
	v_lshlrev_b32_e32 v83, 2, v0
	v_lshlrev_b32_e32 v2, 1, v68
	s_add_u32 s42, s56, 0x280000
	v_and_b32_e32 v1, 28, v83
	v_and_b32_e32 v2, 16, v2
	s_addc_u32 s43, s57, 0
	v_ashrrev_i32_e32 v82, 6, v68
	v_or_b32_e32 v3, v2, v1
	v_add3_u32 v2, v1, v2, 16
	v_cmp_gt_u32_e32 vcc, 16, v1
	s_add_u32 s56, s50, 0x3660000
	v_mul_lo_u32 v1, v82, s94
	v_cndmask_b32_e32 v87, v2, v3, vcc
	v_lshlrev_b32_e32 v2, 4, v0
	v_mov_b32_e32 v0, 2
	s_addc_u32 s57, s51, 0
	v_add3_u32 v88, 0, v1, v2
	v_lshlrev_b32_sdwa v0, v0, v68 dst_sel:DWORD dst_unused:UNUSED_PAD src0_sel:DWORD src1_sel:BYTE_0
	v_mov_b32_e32 v1, 0
	s_add_u32 s54, s54, 0x1e0000
	v_add_u32_e32 v89, 0, v0
	v_lshl_add_u64 v[70:71], s[14:15], 0, v[0:1]
	s_addc_u32 s55, s55, 0
	v_max_i32_e32 v0, 0x7f8, v82
	s_add_u32 s62, s50, 0x3420000
	v_sub_u32_e32 v0, v0, v82
	s_addc_u32 s63, s51, 0
	v_add_u32_e32 v0, 7, v0
	v_writelane_b32 v253, s6, 15
	s_add_u32 s80, s80, 0x2e80000
	v_lshrrev_b32_e32 v3, 3, v0
	s_mov_b32 s27, 0xc000
	v_writelane_b32 v253, s7, 16
	s_addc_u32 s81, s81, 0
	v_add_u32_e32 v3, 1, v3
	v_mad_i64_i32 v[4:5], s[6:7], v82, s27, 0
	s_add_u32 s84, s50, 0x1b20000
	v_and_b32_e32 v6, 7, v3
	v_mov_b32_e32 v3, v1
	v_or_b32_e32 v4, v4, v2
	s_movk_i32 s2, 0x2800
	s_movk_i32 s4, 0x800
	s_movk_i32 s97, 0x500
	s_addc_u32 s85, s51, 0
	v_and_b32_e32 v7, 56, v0
	v_ashrrev_i32_e32 v69, 31, v68
	v_lshl_add_u64 v[4:5], s[76:77], 0, v[4:5]
	s_mov_b64 s[6:7], 0x6000000
	v_lshl_add_u64 v[2:3], s[76:77], 0, v[2:3]
	s_add_i32 s20, 0, 0x22040
	v_and_b32_e32 v84, 0x7c, v83
	v_or_b32_e32 v85, 0xffff9c00, v83
	v_or_b32_e32 v86, 0xffffa000, v83
	v_cmp_gt_i32_e64 s[2:3], s2, v68
	v_cmp_gt_i32_e64 s[4:5], s4, v82
	s_mov_b32 s96, 0x3ffffffd
	v_add_u32_e32 v91, 0xfffffe80, v82
	v_lshl_add_u32 v92, v68, 2, 0
	v_lshl_add_u64 v[72:73], v[68:69], 2, s[70:71]
	v_lshl_add_u32 v69, v82, 2, 0
	v_lshl_add_u64 v[74:75], v[4:5], 0, s[6:7]
	v_sub_u32_e32 v93, 0, v6
	v_lshl_add_u64 v[76:77], v[2:3], 0, s[6:7]
	v_mov_b32_e32 v94, s20
	v_mov_b32_e32 v95, 0xffffea00
	v_mov_b32_e32 v96, 0x80
	s_movk_i32 s21, 0x2000
	v_cmp_gt_i32_e64 s[6:7], s97, v68
	v_cmp_ne_u32_e64 s[8:9], 56, v7
	v_cmp_lt_u32_e64 s[10:11], 55, v0
	s_mov_b64 s[76:77], 0
	s_mov_b64 s[70:71], 0x300000
	s_branch .Ldq1_239
